# merge phase: next tile index fetched one K-segment early (atomic issued ahead, no DMA-queue drain at tile switch)
# speedup vs baseline: 1.0025x; 1.0025x over previous
.LBB0_1013:
	s_waitcnt lgkmcnt(0)
	s_andn2_b64 vcc, exec, s[26:27]
	s_barrier
	s_cbranch_vccnz .LBB0_1063
	s_add_i32 s28, s34, s50
	v_lshl_add_u64 v[226:227], s[18:19], 0, v[166:167]
	s_mov_b32 m0, s28
	v_cndmask_b32_e64 v228, v168, v172, s[22:23]
	global_load_lds_dwordx4 v[226:227], off
	s_add_i32 m0, s28, 0x2000
	s_add_u32 s26, s18, 0x40000
	v_lshl_add_u64 v[226:227], s[18:19], 0, v[168:169]
	s_addc_u32 s27, s19, 0
	global_load_lds_dwordx4 v[226:227], off
	v_lshl_add_u64 v[226:227], s[26:27], 0, v[166:167]
	s_add_i32 m0, s28, 0x4000
	v_mov_b32_e32 v229, v0
	global_load_lds_dwordx4 v[226:227], off
	v_lshl_add_u64 v[226:227], s[26:27], 0, v[168:169]
	s_add_i32 m0, s28, 0x6000
	s_add_i32 s38, s38, 1
	global_load_lds_dwordx4 v[226:227], off
	v_cndmask_b32_e64 v226, v166, v170, s[22:23]
	v_mov_b32_e32 v227, v0
	s_add_i32 m0, s28, 0x8000
	v_lshl_add_u64 v[226:227], s[20:21], 0, v[226:227]
	global_load_lds_dwordx4 v[226:227], off
	v_lshl_add_u64 v[226:227], s[20:21], 0, v[228:229]
	s_add_i32 m0, s28, 0xa000
	s_add_u32 s18, s18, 0x80
	global_load_lds_dwordx4 v[226:227], off
	s_addc_u32 s19, s19, 0
	s_add_u32 s20, s20, 0x80
	s_addc_u32 s21, s21, 0
	s_cmp_lg_u32 s38, s57
	s_mov_b64 s[26:27], -1
	s_cbranch_scc1 .LBB0_1062
	s_add_i32 s37, s37, 1
	s_cmp_lg_u32 s37, 5
	s_cbranch_scc1 .Lm3_noearly
	v_readlane_b32 vcc_lo, v253, 26
	v_readlane_b32 vcc_hi, v253, 27
	s_nop 1
	s_and_saveexec_b64 s[98:99], vcc
	s_cbranch_execz .Lm3_early_done
	v_mov_b32_e32 v163, 1
	global_atomic_add v162, v0, v163, s[16:17] sc0
.Lm3_early_done:
	s_or_b64 exec, exec, s[98:99]
.Lm3_noearly:
	s_cmp_lg_u32 s37, 6
	s_mov_b64 s[28:29], -1
	s_cbranch_scc1 .LBB0_1051
	v_readlane_b32 s0, v253, 26
	v_readlane_b32 s1, v253, 27
	s_and_saveexec_b64 s[26:27], s[0:1]
	s_cbranch_execz .LBB0_1048
	s_mov_b64 s[30:31], exec
	v_mbcnt_lo_u32_b32 v186, s30, 0
	v_mbcnt_hi_u32_b32 v195, s31, v186
	v_cmp_eq_u32_e32 vcc, 0, v195
	s_and_saveexec_b64 s[28:29], vcc
	s_cbranch_execz .LBB0_1019
	s_bcnt1_i32_b64 s30, s[30:31]
	v_mov_b32_e32 v186, s30
	v_mov_b32_e32 v226, v162
.LBB0_1019:
	s_or_b64 exec, exec, s[28:29]
	s_nop 0
	v_readfirstlane_b32 s28, v226
	s_movk_i32 s0, 0x7f
	s_nop 0
	v_add_u32_e32 v186, s28, v195
	v_cmp_lt_i32_e32 vcc, s0, v186
	v_and_b32_e32 v187, 0xffffffe0, v186
	v_readlane_b32 s0, v252, 8
	s_nop 1
	v_add_u32_e32 v187, s0, v187
	v_and_or_b32 v195, v186, 31, v187
	s_and_saveexec_b64 s[28:29], vcc
	s_cbranch_execz .LBB0_1047
	s_mov_b64 s[34:35], exec
	v_mbcnt_lo_u32_b32 v186, s34, 0
	v_mbcnt_hi_u32_b32 v195, s35, v186
	v_cmp_eq_u32_e32 vcc, 0, v195
	s_and_saveexec_b64 s[30:31], vcc
	s_cbranch_execz .LBB0_1022
	s_bcnt1_i32_b64 s34, s[34:35]
	v_mov_b32_e32 v186, s34
	global_atomic_add v226, v0, v186, s[70:71] sc0

.LBB0_1048:
	s_or_b64 exec, exec, s[26:27]
	v_readlane_b32 s0, v253, 5
	s_waitcnt lgkmcnt(0)
	s_barrier
	v_mov_b32_e32 v186, s0
	ds_read_b32 v186, v186
	s_mov_b64 s[28:29], 0
	s_waitcnt lgkmcnt(0)
	s_barrier
	v_cmp_lt_i32_e32 vcc, s64, v186
	v_readfirstlane_b32 s36, v186
	s_cbranch_vccnz .LBB0_1050
	s_add_i32 s51, s51, 1
	s_mov_b64 s[28:29], -1
